# prologue W_in conversion loop: next tile's loads stay in flight across the current tile's LDS transpose (counted vmcnt instead of vmcnt(0))
# speedup vs baseline: 1.0115x; 1.0004x over previous
; #define LAS __attribute__((address_space(3)))
; __device__ __forceinline__ int tidx() { int t = threadIdx.x; asm volatile("" : "+v"(t)); return t; }
; __device__ __forceinline__ void tile_load(const TileJob& j, f32x4 (&v)[2]) {
;     const int tid = tidx(), k0 = j.tk * 64, n0 = j.tn * 64;
; #pragma unroll
;     for (int i = 0; i < 2; ++i) { const int r = (tid >> 4) + 32 * i, c = (tid & 15) * 4, n = n0 + c;
;         v[i] = (f32x4){0.f, 0.f, 0.f, 0.f};
;         if (n < j.Nreal) v[i] = *(const f32x4*)(j.W + (size_t)(k0 + r) * j.Nreal + n); }
; }
; __device__ __forceinline__ void tile_store(const TileJob& j, const f32x4 (&v)[2], LAS float* tile) {
;     const int tid = tidx(), k0 = j.tk * 64, n0 = j.tn * 64;
; #pragma unroll
;     for (int i = 0; i < 2; ++i) { const int r = (tid >> 4) + 32 * i, c = (tid & 15) * 4;
;         tile[r * 65 + c] = v[i][0]; tile[r * 65 + c + 1] = v[i][1]; tile[r * 65 + c + 2] = v[i][2]; tile[r * 65 + c + 3] = v[i][3]; }
;     __syncthreads();
;     { const int nl = tid >> 3, k8 = (tid & 7) * 8; u32x4 w;
;       w.x = pkh(tile[(k8 + 0) * 65 + nl], tile[(k8 + 1) * 65 + nl]); w.y = pkh(tile[(k8 + 2) * 65 + nl], tile[(k8 + 3) * 65 + nl]);
;       w.z = pkh(tile[(k8 + 4) * 65 + nl], tile[(k8 + 5) * 65 + nl]); w.w = pkh(tile[(k8 + 6) * 65 + nl], tile[(k8 + 7) * 65 + nl]);
;       *(u32x4*)(j.Bt + (size_t)(n0 + nl) * j.Kdim + k0 + k8) = w; }
;     __syncthreads();
; }
; __device__ __forceinline__ void convert_tiles(int t0, int t1, int step, LAS float* tile) {
;     int t = t0;
;     if (t < t1) {
;         TileJob cur = tile_job(t); f32x4 v[2]; tile_load(cur, v);
;         for (;;) {
;             const int tn = t + step; const bool more = tn < t1;
;             TileJob nxt = cur; f32x4 vn[2];
;             if (more) { nxt = tile_job(tn); tile_load(nxt, vn); }
;             tile_store(cur, v, tile);
;             if (!more) break;
;             cur = nxt; v[0] = vn[0]; v[1] = vn[1]; t = tn;
;         }
;     }
.LBB0_1004:
	s_or_b64 exec, exec, s[10:11]
	s_lshl_b32 s6, s25, 4
	s_sub_i32 s6, s2, s6
	s_waitcnt vmcnt(2)
.LBB0_1005:
	v_mov_b32_e32 v16, v202
	s_lshl_b32 s8, s12, 6
	v_ashrrev_i32_e32 v22, 4, v16
	v_lshlrev_b32_e32 v23, 4, v16
	v_and_b32_e32 v23, 0xf0, v23
	v_mul_lo_u32 v22, v22, s37
	v_add3_u32 v22, 0, v23, v22
	ds_write2_b32 v22, v0, v1 offset1:1
	ds_write2_b32 v22, v2, v3 offset0:2 offset1:3
	v_add_u32_e32 v0, 0x2080, v22
	ds_write2_b32 v0, v4, v5 offset1:1
	v_add_u32_e32 v0, 0x2088, v22
	ds_write2_b32 v0, v6, v7 offset1:1
	v_lshlrev_b32_e32 v0, 3, v16
	v_ashrrev_i32_e32 v22, 3, v16
	v_and_b32_e32 v16, 56, v0
	v_mul_u32_u24_e32 v0, 0x104, v16
	v_lshlrev_b32_e32 v1, 2, v22
	v_add3_u32 v4, 0, v0, v1
	s_waitcnt lgkmcnt(0)
	s_barrier
	ds_read2_b32 v[0:1], v4 offset1:65
	ds_read2_b32 v[2:3], v4 offset0:130 offset1:195
	v_add_u32_e32 v6, 0x400, v4
	ds_read2_b32 v[4:5], v6 offset0:4 offset1:69
	ds_read2_b32 v[6:7], v6 offset0:134 offset1:199
	s_ashr_i32 s9, s8, 31
	s_waitcnt lgkmcnt(3)
	v_cvt_pk_f16_f32 v0, v0, v1
	s_waitcnt lgkmcnt(2)
	v_cvt_pk_f16_f32 v1, v2, v3
	s_waitcnt lgkmcnt(1)
	v_cvt_pk_f16_f32 v2, v4, v5
	v_lshl_add_u32 v4, s3, 6, v22
	v_ashrrev_i32_e32 v5, 31, v4
	v_lshlrev_b64 v[4:5], 11, v[4:5]
	v_lshl_add_u64 v[4:5], v[18:19], 0, v[4:5]
	v_lshl_add_u64 v[4:5], s[8:9], 1, v[4:5]
	v_lshlrev_b32_e32 v16, 1, v16
	s_waitcnt lgkmcnt(0)
	v_cvt_pk_f16_f32 v3, v6, v7
	v_lshl_add_u64 v[4:5], v[4:5], 0, v[16:17]
	global_store_dwordx4 v[4:5], v[0:3], off
	s_add_i32 s13, s13, s22
	s_andn2_b64 vcc, exec, s[4:5]
	s_mov_b32 s3, s25
	s_mov_b32 s12, s6
	v_mov_b64_e32 v[18:19], v[20:21]
	s_waitcnt vmcnt(1)
	v_mov_b32_e32 v0, v8
	v_mov_b32_e32 v1, v9
	v_mov_b32_e32 v2, v10
	v_mov_b32_e32 v3, v11
	v_mov_b32_e32 v4, v12
	v_mov_b32_e32 v5, v13
	v_mov_b32_e32 v6, v14
	v_mov_b32_e32 v7, v15
	s_barrier
	s_cbranch_vccz .LBB0_1011

; __device__ __forceinline__ void convert_tiles(int t0, int t1, int step, LAS float* tile) {
;     ...
;         TileJob cur = tile_job(t); f32x4 v[2]; tile_load(cur, v);
;         for (;;) {
;             const int tn = t + step; const bool more = tn < t1;
;             TileJob nxt = cur; f32x4 vn[2];
;             if (more) { nxt = tile_job(tn); tile_load(nxt, vn); }
;             tile_store(cur, v, tile);
;             if (!more) break;
;             cur = nxt; v[0] = vn[0]; v[1] = vn[1]; t = tn;
;         }
.Lcvt0_last:
	s_waitcnt vmcnt(0)
	s_branch .LBB0_1005
